# first workgroup of each XCD arriving at grid barriers 2 and 5 starts an L2 write-back early, leaving less dirty data for the leader's write-back
# speedup vs baseline: 1.0135x; 1.0022x over previous
.LBB0_329:
	s_or_b64 exec, exec, s[10:11]
	v_cvt_f32_u32_e32 v4, v2
	s_waitcnt vmcnt(0)
	v_readfirstlane_b32 s0, v3
	v_sub_u32_e32 v3, 0, v2
	v_rcp_iflag_f32_e32 v4, v4
	v_add_u32_e32 v5, s0, v1
	v_mul_f32_e32 v4, 0x4f7ffffe, v4
	v_cvt_u32_f32_e32 v4, v4
	v_mul_lo_u32 v1, v3, v4
	v_mul_hi_u32 v1, v4, v1
	v_add_u32_e32 v1, v4, v1
	v_mul_hi_u32 v1, v5, v1
	v_mul_lo_u32 v3, v1, v2
	v_sub_u32_e32 v3, v5, v3
	v_add_u32_e32 v4, 1, v1
	v_cmp_ge_u32_e32 vcc, v3, v2
	s_nop 1
	v_cndmask_b32_e32 v1, v1, v4, vcc
	v_sub_u32_e32 v4, v3, v2
	v_cndmask_b32_e32 v3, v3, v4, vcc
	v_add_u32_e32 v4, 1, v1
	v_cmp_ge_u32_e32 vcc, v3, v2
	v_add_u32_e32 v3, 1, v5
	s_nop 0
	v_cndmask_b32_e32 v1, v1, v4, vcc
	v_mul_lo_u32 v4, v2, v1
	v_add_u32_e32 v2, v4, v2
	v_add_u32_e32 v4, 1, v4
	v_cmp_eq_u32_e32 vcc, v3, v4
	s_cbranch_vccz .Lewb_0
	buffer_wbl2 sc1
.Lewb_0:
	v_cmp_ne_u32_e32 vcc, v3, v2
	s_and_saveexec_b64 s[8:9], vcc
	s_xor_b64 s[8:9], exec, s[8:9]
	s_cbranch_execz .LBB0_343
	s_waitcnt lgkmcnt(0)
	v_mov_b32_e32 v0, 0x2000
	global_load_dword v0, v0, s[6:7] offset:1024 sc1
	s_add_u32 s28, s6, 0x2400
	s_addc_u32 s29, s7, 0
	s_waitcnt vmcnt(0)
	v_cmp_eq_u32_e32 vcc, v0, v1
	s_and_saveexec_b64 s[10:11], vcc
	s_cbranch_execz .LBB0_342
	s_add_u32 s12, s58, 0xfd29200
	s_addc_u32 s13, s59, 0
	s_mov_b32 s2, 1
	s_mov_b64 s[30:31], 0
	v_mov_b32_e32 v0, 0
	s_branch .LBB0_333

.Lewb_1:
	v_cmp_ne_u32_e32 vcc, v3, v2
	s_and_saveexec_b64 s[0:1], vcc
	s_xor_b64 s[8:9], exec, s[0:1]
	s_cbranch_execz .LBB0_756
	s_waitcnt lgkmcnt(0)
	v_mov_b32_e32 v0, 0x2000
	global_load_dword v0, v0, s[6:7] offset:1024 sc1
	s_add_u32 s14, s6, 0x2400
	s_addc_u32 s15, s7, 0
	s_waitcnt vmcnt(0)
	v_cmp_eq_u32_e32 vcc, v0, v1
	s_and_saveexec_b64 s[10:11], vcc
	s_cbranch_execz .LBB0_755
	s_add_u32 s12, s58, 0xfd29200
	s_addc_u32 s13, s59, 0
	s_mov_b32 s2, 1
	s_mov_b64 s[16:17], 0
	v_mov_b32_e32 v0, 0
	s_branch .LBB0_746
